# v098 with the per-token P10 barrier moved to just before the first u-sweep loop (after its first row group loads are issued)
# speedup vs baseline: 1.0082x; 1.0015x over previous
; __device__ __forceinline__ float bf_lo(unsigned u) { return __uint_as_float(u << 16); }
; __device__ __forceinline__ float bf_hi(unsigned u) { return __uint_as_float(u & 0xffff0000u); }
; __global__ void __launch_bounds__(NT, 2) mk_fwd(Args args) {
;     ...
;             for (int j = 0; j < 4; ++j) { const u32x4 a = *(const u32x4*)(HB + (size_t)tok * DM + lane * 32 + j * 8);
; #pragma unroll
;                 for (int q = 0; q < 4; ++q) hf2[j * 4 + q] = (f32x2){bf_lo(a[q]), bf_hi(a[q])}; }
;             const int e0 = EIDX[(size_t)tok * 128 + lane], e1 = EIDX[(size_t)tok * 128 + 64 + lane];
;             const float g0 = GATE[(size_t)tok * 128 + lane], g1 = GATE[(size_t)tok * 128 + 64 + lane];
;             const bool hi32 = (lane & 32) != 0, hi16 = (lane & 16) != 0; const int l3 = (lane & 3) << 4;
.LBB0_886:
	s_ashr_i32 s71, s70, 31
	s_lshl_b64 s[4:5], s[70:71], 9
	v_lshl_or_b32 v0, v128, 2, s4
	v_mov_b32_e32 v1, s5
	v_lshl_add_u64 v[2:3], s[46:47], 0, v[0:1]
	global_load_dword v108, v[2:3], off
	s_lshl_b64 s[4:5], s[70:71], 12
	v_lshl_add_u64 v[2:3], v[96:97], 0, s[4:5]
	global_load_dwordx4 v[32:35], v[2:3], off offset:48
	global_load_dwordx4 v[36:39], v[2:3], off offset:32
	global_load_dwordx4 v[40:43], v[2:3], off offset:16
	global_load_dwordx4 v[44:47], v[2:3], off
	v_or_b32_e32 v2, 0x100, v0
	v_mov_b32_e32 v3, v1
	v_lshl_add_u64 v[0:1], s[48:49], 0, v[0:1]
	v_lshl_add_u64 v[4:5], s[46:47], 0, v[2:3]
	v_lshl_add_u64 v[2:3], s[48:49], 0, v[2:3]
	global_load_dword v106, v[4:5], off
	global_load_dword v110, v[0:1], off
	global_load_dword v156, v[2:3], off
	s_waitcnt vmcnt(0)
	v_lshl_or_b32 v170, v108, 7, v128
	v_lshlrev_b32_e32 v171, 7, v106
	v_or_b32_e32 v174, 64, v128
	v_or_b32_e32 v171, v171, v174
	s_nop 0
	s_xnor_b64 s[62:63], s[50:51], s[52:53]
	s_nop 1
	v_min_u32_dpp v172, v170, v170 quad_perm:[1,0,3,2] row_mask:0xf bank_mask:0xf
	v_max_u32_dpp v173, v170, v170 quad_perm:[1,0,3,2] row_mask:0xf bank_mask:0xf
	v_min_u32_dpp v175, v171, v171 quad_perm:[1,0,3,2] row_mask:0xf bank_mask:0xf
	v_max_u32_dpp v176, v171, v171 quad_perm:[1,0,3,2] row_mask:0xf bank_mask:0xf
	v_cndmask_b32_e64 v170, v173, v172, s[62:63]
	v_cndmask_b32_e64 v171, v176, v175, s[62:63]
	s_xnor_b64 s[62:63], s[52:53], s[54:55]
	s_nop 1
	v_min_u32_dpp v172, v170, v170 quad_perm:[2,3,0,1] row_mask:0xf bank_mask:0xf
	v_max_u32_dpp v173, v170, v170 quad_perm:[2,3,0,1] row_mask:0xf bank_mask:0xf
	v_min_u32_dpp v175, v171, v171 quad_perm:[2,3,0,1] row_mask:0xf bank_mask:0xf
	v_max_u32_dpp v176, v171, v171 quad_perm:[2,3,0,1] row_mask:0xf bank_mask:0xf
	v_cndmask_b32_e64 v170, v173, v172, s[62:63]
	v_cndmask_b32_e64 v171, v176, v175, s[62:63]
	s_xnor_b64 s[62:63], s[50:51], s[54:55]
	s_nop 1
	v_min_u32_dpp v172, v170, v170 quad_perm:[1,0,3,2] row_mask:0xf bank_mask:0xf
	v_max_u32_dpp v173, v170, v170 quad_perm:[1,0,3,2] row_mask:0xf bank_mask:0xf
	v_min_u32_dpp v175, v171, v171 quad_perm:[1,0,3,2] row_mask:0xf bank_mask:0xf
	v_max_u32_dpp v176, v171, v171 quad_perm:[1,0,3,2] row_mask:0xf bank_mask:0xf
	v_cndmask_b32_e64 v170, v173, v172, s[62:63]
	v_cndmask_b32_e64 v171, v176, v175, s[62:63]
	s_xnor_b64 s[62:63], s[54:55], s[56:57]
	s_nop 1
	v_mov_b32_dpp v174, v170 row_half_mirror row_mask:0xf bank_mask:0xf
	v_mov_b32_dpp v177, v171 row_half_mirror row_mask:0xf bank_mask:0xf
	s_nop 0
	v_min_u32_dpp v172, v174, v170 quad_perm:[3,2,1,0] row_mask:0xf bank_mask:0xf
	v_max_u32_dpp v173, v174, v170 quad_perm:[3,2,1,0] row_mask:0xf bank_mask:0xf
	v_min_u32_dpp v175, v177, v171 quad_perm:[3,2,1,0] row_mask:0xf bank_mask:0xf
	v_max_u32_dpp v176, v177, v171 quad_perm:[3,2,1,0] row_mask:0xf bank_mask:0xf
	v_cndmask_b32_e64 v170, v173, v172, s[62:63]
	v_cndmask_b32_e64 v171, v176, v175, s[62:63]
	s_xnor_b64 s[62:63], s[52:53], s[56:57]
	s_nop 1
	v_min_u32_dpp v172, v170, v170 quad_perm:[2,3,0,1] row_mask:0xf bank_mask:0xf
	v_max_u32_dpp v173, v170, v170 quad_perm:[2,3,0,1] row_mask:0xf bank_mask:0xf
	v_min_u32_dpp v175, v171, v171 quad_perm:[2,3,0,1] row_mask:0xf bank_mask:0xf
	v_max_u32_dpp v176, v171, v171 quad_perm:[2,3,0,1] row_mask:0xf bank_mask:0xf
	v_cndmask_b32_e64 v170, v173, v172, s[62:63]
	v_cndmask_b32_e64 v171, v176, v175, s[62:63]
	s_xnor_b64 s[62:63], s[50:51], s[56:57]
	s_nop 1
	v_min_u32_dpp v172, v170, v170 quad_perm:[1,0,3,2] row_mask:0xf bank_mask:0xf
	v_max_u32_dpp v173, v170, v170 quad_perm:[1,0,3,2] row_mask:0xf bank_mask:0xf
	v_min_u32_dpp v175, v171, v171 quad_perm:[1,0,3,2] row_mask:0xf bank_mask:0xf
	v_max_u32_dpp v176, v171, v171 quad_perm:[1,0,3,2] row_mask:0xf bank_mask:0xf
	v_cndmask_b32_e64 v170, v173, v172, s[62:63]
	v_cndmask_b32_e64 v171, v176, v175, s[62:63]
	s_xnor_b64 s[62:63], s[56:57], s[58:59]
	s_nop 1
	v_min_u32_dpp v172, v170, v170 row_ror:8 row_mask:0xf bank_mask:0xf
	v_max_u32_dpp v173, v170, v170 row_ror:8 row_mask:0xf bank_mask:0xf
	v_min_u32_dpp v175, v171, v171 row_ror:8 row_mask:0xf bank_mask:0xf
	v_max_u32_dpp v176, v171, v171 row_ror:8 row_mask:0xf bank_mask:0xf
	v_cndmask_b32_e64 v170, v173, v172, s[62:63]
	v_cndmask_b32_e64 v171, v176, v175, s[62:63]
	s_xnor_b64 s[62:63], s[54:55], s[58:59]
	s_nop 1
	v_mov_b32_dpp v174, v170 row_half_mirror row_mask:0xf bank_mask:0xf
	v_mov_b32_dpp v177, v171 row_half_mirror row_mask:0xf bank_mask:0xf
	s_nop 0
	v_min_u32_dpp v172, v174, v170 quad_perm:[3,2,1,0] row_mask:0xf bank_mask:0xf
	v_max_u32_dpp v173, v174, v170 quad_perm:[3,2,1,0] row_mask:0xf bank_mask:0xf
	v_min_u32_dpp v175, v177, v171 quad_perm:[3,2,1,0] row_mask:0xf bank_mask:0xf
	v_max_u32_dpp v176, v177, v171 quad_perm:[3,2,1,0] row_mask:0xf bank_mask:0xf
	v_cndmask_b32_e64 v170, v173, v172, s[62:63]
	v_cndmask_b32_e64 v171, v176, v175, s[62:63]
	s_xnor_b64 s[62:63], s[52:53], s[58:59]
	s_nop 1
	v_min_u32_dpp v172, v170, v170 quad_perm:[2,3,0,1] row_mask:0xf bank_mask:0xf
	v_max_u32_dpp v173, v170, v170 quad_perm:[2,3,0,1] row_mask:0xf bank_mask:0xf
	v_min_u32_dpp v175, v171, v171 quad_perm:[2,3,0,1] row_mask:0xf bank_mask:0xf
	v_max_u32_dpp v176, v171, v171 quad_perm:[2,3,0,1] row_mask:0xf bank_mask:0xf
	v_cndmask_b32_e64 v170, v173, v172, s[62:63]
	v_cndmask_b32_e64 v171, v176, v175, s[62:63]
	s_xnor_b64 s[62:63], s[50:51], s[58:59]
	s_nop 1
	v_min_u32_dpp v172, v170, v170 quad_perm:[1,0,3,2] row_mask:0xf bank_mask:0xf
	v_max_u32_dpp v173, v170, v170 quad_perm:[1,0,3,2] row_mask:0xf bank_mask:0xf
	v_min_u32_dpp v175, v171, v171 quad_perm:[1,0,3,2] row_mask:0xf bank_mask:0xf
	v_max_u32_dpp v176, v171, v171 quad_perm:[1,0,3,2] row_mask:0xf bank_mask:0xf
	v_cndmask_b32_e64 v170, v173, v172, s[62:63]
	v_cndmask_b32_e64 v171, v176, v175, s[62:63]
	s_xnor_b64 s[62:63], s[58:59], s[60:61]
	ds_bpermute_b32 v174, v146, v170
	ds_bpermute_b32 v177, v146, v171
	s_waitcnt lgkmcnt(1)
; __global__ void __launch_bounds__(NT, 2) mk_fwd(Args args) {
;     ...
;             const int e0 = EIDX[(size_t)tok * 128 + lane], e1 = EIDX[(size_t)tok * 128 + 64 + lane];
;             const float g0 = GATE[(size_t)tok * 128 + lane], g1 = GATE[(size_t)tok * 128 + 64 + lane];
	v_min_u32_e32 v172, v174, v170
	v_max_u32_e32 v173, v174, v170
	s_waitcnt lgkmcnt(0)
	v_min_u32_e32 v175, v177, v171
	v_max_u32_e32 v176, v177, v171
	v_cndmask_b32_e64 v170, v173, v172, s[62:63]
	v_cndmask_b32_e64 v171, v176, v175, s[62:63]
	s_xnor_b64 s[62:63], s[56:57], s[60:61]
	s_nop 1
	v_min_u32_dpp v172, v170, v170 row_ror:8 row_mask:0xf bank_mask:0xf
	v_max_u32_dpp v173, v170, v170 row_ror:8 row_mask:0xf bank_mask:0xf
	v_min_u32_dpp v175, v171, v171 row_ror:8 row_mask:0xf bank_mask:0xf
	v_max_u32_dpp v176, v171, v171 row_ror:8 row_mask:0xf bank_mask:0xf
	v_cndmask_b32_e64 v170, v173, v172, s[62:63]
	v_cndmask_b32_e64 v171, v176, v175, s[62:63]
	s_xnor_b64 s[62:63], s[54:55], s[60:61]
	s_nop 1
	v_mov_b32_dpp v174, v170 row_half_mirror row_mask:0xf bank_mask:0xf
	v_mov_b32_dpp v177, v171 row_half_mirror row_mask:0xf bank_mask:0xf
	s_nop 0
	v_min_u32_dpp v172, v174, v170 quad_perm:[3,2,1,0] row_mask:0xf bank_mask:0xf
	v_max_u32_dpp v173, v174, v170 quad_perm:[3,2,1,0] row_mask:0xf bank_mask:0xf
	v_min_u32_dpp v175, v177, v171 quad_perm:[3,2,1,0] row_mask:0xf bank_mask:0xf
	v_max_u32_dpp v176, v177, v171 quad_perm:[3,2,1,0] row_mask:0xf bank_mask:0xf
	v_cndmask_b32_e64 v170, v173, v172, s[62:63]
	v_cndmask_b32_e64 v171, v176, v175, s[62:63]
	s_xnor_b64 s[62:63], s[52:53], s[60:61]
	s_nop 1
	v_min_u32_dpp v172, v170, v170 quad_perm:[2,3,0,1] row_mask:0xf bank_mask:0xf
	v_max_u32_dpp v173, v170, v170 quad_perm:[2,3,0,1] row_mask:0xf bank_mask:0xf
	v_min_u32_dpp v175, v171, v171 quad_perm:[2,3,0,1] row_mask:0xf bank_mask:0xf
	v_max_u32_dpp v176, v171, v171 quad_perm:[2,3,0,1] row_mask:0xf bank_mask:0xf
	v_cndmask_b32_e64 v170, v173, v172, s[62:63]
	v_cndmask_b32_e64 v171, v176, v175, s[62:63]
	s_xnor_b64 s[62:63], s[50:51], s[60:61]
	s_nop 1
	v_min_u32_dpp v172, v170, v170 quad_perm:[1,0,3,2] row_mask:0xf bank_mask:0xf
	v_max_u32_dpp v173, v170, v170 quad_perm:[1,0,3,2] row_mask:0xf bank_mask:0xf
	v_min_u32_dpp v175, v171, v171 quad_perm:[1,0,3,2] row_mask:0xf bank_mask:0xf
	v_max_u32_dpp v176, v171, v171 quad_perm:[1,0,3,2] row_mask:0xf bank_mask:0xf
	v_cndmask_b32_e64 v170, v173, v172, s[62:63]
	v_cndmask_b32_e64 v171, v176, v175, s[62:63]
	ds_bpermute_b32 v174, v129, v170
	ds_bpermute_b32 v177, v129, v171
	s_waitcnt lgkmcnt(1)
	v_min_u32_e32 v172, v174, v170
	v_max_u32_e32 v173, v174, v170
	s_waitcnt lgkmcnt(0)
	v_min_u32_e32 v175, v177, v171
	v_max_u32_e32 v176, v177, v171
	v_cndmask_b32_e64 v170, v173, v172, s[60:61]
	v_cndmask_b32_e64 v171, v175, v176, s[60:61]
	ds_bpermute_b32 v174, v146, v170
	ds_bpermute_b32 v177, v146, v171
	s_waitcnt lgkmcnt(1)
	v_min_u32_e32 v172, v174, v170
	v_max_u32_e32 v173, v174, v170
	s_waitcnt lgkmcnt(0)
	v_min_u32_e32 v175, v177, v171
	v_max_u32_e32 v176, v177, v171
	v_cndmask_b32_e64 v170, v173, v172, s[58:59]
	v_cndmask_b32_e64 v171, v175, v176, s[58:59]
	s_nop 1
	v_min_u32_dpp v172, v170, v170 row_ror:8 row_mask:0xf bank_mask:0xf
	v_max_u32_dpp v173, v170, v170 row_ror:8 row_mask:0xf bank_mask:0xf
	v_min_u32_dpp v175, v171, v171 row_ror:8 row_mask:0xf bank_mask:0xf
	v_max_u32_dpp v176, v171, v171 row_ror:8 row_mask:0xf bank_mask:0xf
	v_cndmask_b32_e64 v170, v173, v172, s[56:57]
	v_cndmask_b32_e64 v171, v175, v176, s[56:57]
	s_nop 1
	v_mov_b32_dpp v174, v170 row_half_mirror row_mask:0xf bank_mask:0xf
	v_mov_b32_dpp v177, v171 row_half_mirror row_mask:0xf bank_mask:0xf
	s_nop 0
	v_min_u32_dpp v172, v174, v170 quad_perm:[3,2,1,0] row_mask:0xf bank_mask:0xf
	v_max_u32_dpp v173, v174, v170 quad_perm:[3,2,1,0] row_mask:0xf bank_mask:0xf
	v_min_u32_dpp v175, v177, v171 quad_perm:[3,2,1,0] row_mask:0xf bank_mask:0xf
	v_max_u32_dpp v176, v177, v171 quad_perm:[3,2,1,0] row_mask:0xf bank_mask:0xf
	v_cndmask_b32_e64 v170, v173, v172, s[54:55]
	v_cndmask_b32_e64 v171, v175, v176, s[54:55]
	s_nop 1
	v_min_u32_dpp v172, v170, v170 quad_perm:[2,3,0,1] row_mask:0xf bank_mask:0xf
	v_max_u32_dpp v173, v170, v170 quad_perm:[2,3,0,1] row_mask:0xf bank_mask:0xf
	v_min_u32_dpp v175, v171, v171 quad_perm:[2,3,0,1] row_mask:0xf bank_mask:0xf
	v_max_u32_dpp v176, v171, v171 quad_perm:[2,3,0,1] row_mask:0xf bank_mask:0xf
	v_cndmask_b32_e64 v170, v173, v172, s[52:53]
	v_cndmask_b32_e64 v171, v175, v176, s[52:53]
	s_nop 1
	v_min_u32_dpp v172, v170, v170 quad_perm:[1,0,3,2] row_mask:0xf bank_mask:0xf
	v_max_u32_dpp v173, v170, v170 quad_perm:[1,0,3,2] row_mask:0xf bank_mask:0xf
	v_min_u32_dpp v175, v171, v171 quad_perm:[1,0,3,2] row_mask:0xf bank_mask:0xf
	v_max_u32_dpp v176, v171, v171 quad_perm:[1,0,3,2] row_mask:0xf bank_mask:0xf
	v_cndmask_b32_e64 v170, v173, v172, s[50:51]
	v_cndmask_b32_e64 v171, v175, v176, s[50:51]
	v_min_u32_e32 v172, v170, v171
	v_max_u32_e32 v171, v170, v171
	v_mov_b32_e32 v170, v172
	ds_bpermute_b32 v174, v129, v170
	ds_bpermute_b32 v177, v129, v171
	s_waitcnt lgkmcnt(1)
	v_min_u32_e32 v172, v174, v170
	v_max_u32_e32 v173, v174, v170
	s_waitcnt lgkmcnt(0)
	v_min_u32_e32 v175, v177, v171
	v_max_u32_e32 v176, v177, v171
	v_cndmask_b32_e64 v170, v173, v172, s[60:61]
	v_cndmask_b32_e64 v171, v176, v175, s[60:61]
	ds_bpermute_b32 v174, v146, v170
	ds_bpermute_b32 v177, v146, v171
	s_waitcnt lgkmcnt(1)
	v_min_u32_e32 v172, v174, v170
	v_max_u32_e32 v173, v174, v170
	s_waitcnt lgkmcnt(0)
; __device__ __forceinline__ float bf_lo(unsigned u) { return __uint_as_float(u << 16); }
; __device__ __forceinline__ float bf_hi(unsigned u) { return __uint_as_float(u & 0xffff0000u); }
; #define PU_LOAD(BUF, EV, S0) do { _Pragma("unroll") for (int i = 0; i < 8; ++i) { const int row_ = __builtin_amdgcn_readlane(EV, (S0) + i); BUF[i & 3][i >> 2] = *(const u32x4*)(PU8 + (size_t)row_ * 1024 + lane * 16); } } while (0)
; __global__ void __launch_bounds__(NT, 2) mk_fwd(Args args) {
;     ...
;             for (int j = 0; j < 4; ++j) { const u32x4 a = *(const u32x4*)(HB + (size_t)tok * DM + lane * 32 + j * 8);
; #pragma unroll
;                 for (int q = 0; q < 4; ++q) hf2[j * 4 + q] = (f32x2){bf_lo(a[q]), bf_hi(a[q])}; }
;             const int e0 = EIDX[(size_t)tok * 128 + lane], e1 = EIDX[(size_t)tok * 128 + 64 + lane];
;             const float g0 = GATE[(size_t)tok * 128 + lane], g1 = GATE[(size_t)tok * 128 + 64 + lane];
;             const bool hi32 = (lane & 32) != 0, hi16 = (lane & 16) != 0; const int l3 = (lane & 3) << 4;
;     ...
;             float act0 = 0.f, act1 = 0.f;
;             u32x4 bA[4][2], bB[4][2];
; #pragma unroll
;             for (int hh = 0; hh < 2; ++hh) {
;                 const int ev = hh ? e1 : e0; const float gv = hh ? g1 : g0; float dv = 0.f;
;                 PU_LOAD(bA, ev, 0);
	v_min_u32_e32 v175, v177, v171
	v_max_u32_e32 v176, v177, v171
	v_cndmask_b32_e64 v170, v173, v172, s[58:59]
	v_cndmask_b32_e64 v171, v176, v175, s[58:59]
	s_nop 1
	v_min_u32_dpp v172, v170, v170 row_ror:8 row_mask:0xf bank_mask:0xf
	v_max_u32_dpp v173, v170, v170 row_ror:8 row_mask:0xf bank_mask:0xf
	v_min_u32_dpp v175, v171, v171 row_ror:8 row_mask:0xf bank_mask:0xf
	v_max_u32_dpp v176, v171, v171 row_ror:8 row_mask:0xf bank_mask:0xf
	v_cndmask_b32_e64 v170, v173, v172, s[56:57]
	v_cndmask_b32_e64 v171, v176, v175, s[56:57]
	s_nop 1
	v_mov_b32_dpp v174, v170 row_half_mirror row_mask:0xf bank_mask:0xf
	v_mov_b32_dpp v177, v171 row_half_mirror row_mask:0xf bank_mask:0xf
	s_nop 0
	v_min_u32_dpp v172, v174, v170 quad_perm:[3,2,1,0] row_mask:0xf bank_mask:0xf
	v_max_u32_dpp v173, v174, v170 quad_perm:[3,2,1,0] row_mask:0xf bank_mask:0xf
	v_min_u32_dpp v175, v177, v171 quad_perm:[3,2,1,0] row_mask:0xf bank_mask:0xf
	v_max_u32_dpp v176, v177, v171 quad_perm:[3,2,1,0] row_mask:0xf bank_mask:0xf
	v_cndmask_b32_e64 v170, v173, v172, s[54:55]
	v_cndmask_b32_e64 v171, v176, v175, s[54:55]
	s_nop 1
	v_min_u32_dpp v172, v170, v170 quad_perm:[2,3,0,1] row_mask:0xf bank_mask:0xf
	v_max_u32_dpp v173, v170, v170 quad_perm:[2,3,0,1] row_mask:0xf bank_mask:0xf
	v_min_u32_dpp v175, v171, v171 quad_perm:[2,3,0,1] row_mask:0xf bank_mask:0xf
	v_max_u32_dpp v176, v171, v171 quad_perm:[2,3,0,1] row_mask:0xf bank_mask:0xf
	v_cndmask_b32_e64 v170, v173, v172, s[52:53]
	v_cndmask_b32_e64 v171, v176, v175, s[52:53]
	s_nop 1
	v_min_u32_dpp v172, v170, v170 quad_perm:[1,0,3,2] row_mask:0xf bank_mask:0xf
	v_max_u32_dpp v173, v170, v170 quad_perm:[1,0,3,2] row_mask:0xf bank_mask:0xf
	v_min_u32_dpp v175, v171, v171 quad_perm:[1,0,3,2] row_mask:0xf bank_mask:0xf
	v_max_u32_dpp v176, v171, v171 quad_perm:[1,0,3,2] row_mask:0xf bank_mask:0xf
	v_cndmask_b32_e64 v170, v173, v172, s[50:51]
	v_cndmask_b32_e64 v171, v176, v175, s[50:51]
	v_and_b32_e32 v172, 63, v170
	v_lshlrev_b32_e32 v172, 2, v172
	ds_bpermute_b32 v173, v172, v110
	ds_bpermute_b32 v174, v172, v156
	v_and_b32_e32 v175, 63, v171
	v_lshlrev_b32_e32 v175, 2, v175
	ds_bpermute_b32 v176, v175, v110
	ds_bpermute_b32 v177, v175, v156
	v_and_b32_e32 v172, 64, v170
	v_cmp_eq_u32_e32 vcc, 0, v172
	s_waitcnt lgkmcnt(2)
	v_lshrrev_b32_e32 v108, 7, v170
	v_cndmask_b32_e32 v178, v174, v173, vcc
	v_and_b32_e32 v175, 64, v171
	v_cmp_eq_u32_e32 vcc, 0, v175
	s_waitcnt lgkmcnt(0)
	v_lshrrev_b32_e32 v106, 7, v171
	v_cndmask_b32_e32 v179, v177, v176, vcc
	v_mov_b32_e32 v110, v178
	v_mov_b32_e32 v156, v179
	v_ashrrev_i32_e32 v181, 31, v108
	v_mov_b32_e32 v180, v108
	v_ashrrev_i32_e32 v183, 31, v106
	v_mov_b32_e32 v182, v106
	v_lshl_add_u64 v[180:181], v[180:181], 2, s[6:7]
	v_lshl_add_u64 v[182:183], v[182:183], 2, s[6:7]
	global_load_dword v218, v[180:181], off
	global_load_dword v219, v[182:183], off
	s_mov_b32 s10, 0
	v_mov_b32_e32 v107, 0
	s_waitcnt vmcnt(6)
	v_lshlrev_b32_e32 v88, 16, v32
	v_readlane_b32 s4, v108, 0
	v_readlane_b32 s30, v108, 1
	v_readlane_b32 s34, v108, 2
	v_readlane_b32 s36, v108, 3
	v_readlane_b32 s38, v108, 4
	v_readlane_b32 s40, v108, 5
	v_readlane_b32 s42, v108, 6
	v_readlane_b32 s44, v108, 7
	s_ashr_i32 s5, s4, 31
	s_ashr_i32 s31, s30, 31
	s_ashr_i32 s35, s34, 31
	s_ashr_i32 s37, s36, 31
	s_ashr_i32 s39, s38, 31
	s_ashr_i32 s41, s40, 31
	s_ashr_i32 s43, s42, 31
	s_ashr_i32 s45, s44, 31
	s_lshl_b64 s[4:5], s[4:5], 10
	s_lshl_b64 s[30:31], s[30:31], 10
	s_lshl_b64 s[34:35], s[34:35], 10
	s_lshl_b64 s[36:37], s[36:37], 10
	s_lshl_b64 s[38:39], s[38:39], 10
	s_lshl_b64 s[40:41], s[40:41], 10
	s_lshl_b64 s[42:43], s[42:43], 10
	s_lshl_b64 s[44:45], s[44:45], 10
	v_lshl_add_u64 v[48:49], v[98:99], 0, s[4:5]
	v_lshl_add_u64 v[50:51], v[98:99], 0, s[30:31]
	v_lshl_add_u64 v[52:53], v[98:99], 0, s[34:35]
	v_lshl_add_u64 v[54:55], v[98:99], 0, s[36:37]
	v_lshl_add_u64 v[56:57], v[98:99], 0, s[38:39]
	v_lshl_add_u64 v[58:59], v[98:99], 0, s[40:41]
	v_lshl_add_u64 v[60:61], v[98:99], 0, s[42:43]
	v_lshl_add_u64 v[62:63], v[98:99], 0, s[44:45]
	global_load_dwordx4 v[0:3], v[48:49], off
	global_load_dwordx4 v[4:7], v[50:51], off
	global_load_dwordx4 v[8:11], v[52:53], off
	global_load_dwordx4 v[12:15], v[54:55], off
	global_load_dwordx4 v[16:19], v[56:57], off
	global_load_dwordx4 v[20:23], v[58:59], off
	global_load_dwordx4 v[24:27], v[60:61], off
	global_load_dwordx4 v[28:31], v[62:63], off
	s_waitcnt vmcnt(11)
	v_lshlrev_b32_e32 v64, 16, v44
	v_and_b32_e32 v65, 0xffff0000, v44
	v_lshlrev_b32_e32 v66, 16, v45
	v_and_b32_e32 v67, 0xffff0000, v45
	v_lshlrev_b32_e32 v68, 16, v46
	v_and_b32_e32 v69, 0xffff0000, v46
	v_lshlrev_b32_e32 v70, 16, v47
	v_and_b32_e32 v71, 0xffff0000, v47
	v_lshlrev_b32_e32 v72, 16, v40
	v_and_b32_e32 v73, 0xffff0000, v40
	v_lshlrev_b32_e32 v74, 16, v41
	v_and_b32_e32 v75, 0xffff0000, v41
	v_lshlrev_b32_e32 v76, 16, v42
	v_and_b32_e32 v77, 0xffff0000, v42
	v_lshlrev_b32_e32 v78, 16, v43
	v_and_b32_e32 v79, 0xffff0000, v43
	v_lshlrev_b32_e32 v80, 16, v36
	v_and_b32_e32 v81, 0xffff0000, v36
	v_lshlrev_b32_e32 v82, 16, v37
	v_and_b32_e32 v83, 0xffff0000, v37
	v_lshlrev_b32_e32 v84, 16, v38
	v_and_b32_e32 v85, 0xffff0000, v38
	v_lshlrev_b32_e32 v86, 16, v39
	v_and_b32_e32 v87, 0xffff0000, v39
	v_and_b32_e32 v89, 0xffff0000, v32
	v_lshlrev_b32_e32 v90, 16, v33
	v_and_b32_e32 v91, 0xffff0000, v33
	v_lshlrev_b32_e32 v92, 16, v34
	v_and_b32_e32 v93, 0xffff0000, v34
	v_lshlrev_b32_e32 v94, 16, v35
	v_and_b32_e32 v95, 0xffff0000, v35
	s_cmp_eq_u32 s84, 0x100
	s_cbranch_scc0 .Lp10_nobar
	s_barrier
; #define PU_LOAD(BUF, EV, S0) do { _Pragma("unroll") for (int i = 0; i < 8; ++i) { const int row_ = __builtin_amdgcn_readlane(EV, (S0) + i); BUF[i & 3][i >> 2] = *(const u32x4*)(PU8 + (size_t)row_ * 1024 + lane * 16); } } while (0)
; __global__ void __launch_bounds__(NT, 2) mk_fwd(Args args) {
;     ...
;             float act0 = 0.f, act1 = 0.f;
;             u32x4 bA[4][2], bB[4][2];
; #pragma unroll
;             for (int hh = 0; hh < 2; ++hh) {
;                 const int ev = hh ? e1 : e0; const float gv = hh ? g1 : g0; float dv = 0.f;
;                 PU_LOAD(bA, ev, 0);
; #pragma unroll 1
;                 for (int s = 0; s < 64; s += 16) {
;                     PU_LOAD(bB, ev, s + 8);
;                     PU_DOT4(bA, 0, s); PU_DOT4(bA, 1, s + 4);
;                     if (s + 16 < 64) PU_LOAD(bA, ev, s + 16);
;                     PU_DOT4(bB, 0, s + 8); PU_DOT4(bB, 1, s + 12);
.Lp10_nobar:
.LBB0_887:
	s_add_i32 s4, s10, 8
	v_readlane_b32 s4, v108, s4
	s_ashr_i32 s5, s4, 31
	s_lshl_b64 s[4:5], s[4:5], 10
	v_lshl_add_u64 v[32:33], v[98:99], 0, s[4:5]
	s_add_i32 s4, s10, 9
	v_readlane_b32 s4, v108, s4
	s_ashr_i32 s5, s4, 31
	s_lshl_b64 s[4:5], s[4:5], 10
	v_lshl_add_u64 v[34:35], v[98:99], 0, s[4:5]
	s_add_i32 s4, s10, 10
	v_readlane_b32 s4, v108, s4
	s_ashr_i32 s5, s4, 31
	s_lshl_b64 s[4:5], s[4:5], 10
	global_load_dwordx4 v[60:63], v[32:33], off
	global_load_dwordx4 v[52:55], v[34:35], off
	v_lshl_add_u64 v[32:33], v[98:99], 0, s[4:5]
	s_add_i32 s4, s10, 11
	v_readlane_b32 s4, v108, s4
	s_ashr_i32 s5, s4, 31
	s_lshl_b64 s[4:5], s[4:5], 10
	v_lshl_add_u64 v[34:35], v[98:99], 0, s[4:5]
	s_add_i32 s4, s10, 12
	v_readlane_b32 s4, v108, s4
	s_ashr_i32 s5, s4, 31
	s_lshl_b64 s[4:5], s[4:5], 10
	v_lshl_add_u64 v[44:45], v[98:99], 0, s[4:5]
	s_add_i32 s4, s10, 13
	v_readlane_b32 s4, v108, s4
	s_ashr_i32 s5, s4, 31
	s_lshl_b64 s[4:5], s[4:5], 10
	v_lshl_add_u64 v[46:47], v[98:99], 0, s[4:5]
	global_load_dwordx4 v[48:51], v[32:33], off
	global_load_dwordx4 v[40:43], v[34:35], off
	global_load_dwordx4 v[36:39], v[44:45], off
	s_nop 0
	global_load_dwordx4 v[32:35], v[46:47], off
	s_waitcnt vmcnt(13)
	v_cvt_scalef32_pk_f32_fp4 v[46:47], v0, 1.0
	v_pk_fma_f32 v[46:47], v[46:47], v[64:65], 0 op_sel_hi:[1,1,0]
	v_cvt_scalef32_pk_f32_fp4 v[56:57], v0, 1.0 op_sel:[1,0,0]
	v_pk_fma_f32 v[46:47], v[56:57], v[66:67], v[46:47]
	v_cvt_scalef32_pk_f32_fp4 v[56:57], v0, 1.0 op_sel:[0,1,0]
	v_pk_fma_f32 v[46:47], v[56:57], v[68:69], v[46:47]
	v_cvt_scalef32_pk_f32_fp4 v[56:57], v0, 1.0 op_sel:[1,1,0]
	v_pk_fma_f32 v[46:47], v[56:57], v[70:71], v[46:47]
	v_cvt_scalef32_pk_f32_fp4 v[56:57], v1, 1.0
	v_pk_fma_f32 v[46:47], v[56:57], v[72:73], v[46:47]
	v_cvt_scalef32_pk_f32_fp4 v[56:57], v1, 1.0 op_sel:[1,0,0]
	v_pk_fma_f32 v[46:47], v[56:57], v[74:75], v[46:47]
	v_cvt_scalef32_pk_f32_fp4 v[56:57], v1, 1.0 op_sel:[0,1,0]
	v_pk_fma_f32 v[46:47], v[56:57], v[76:77], v[46:47]
	v_cvt_scalef32_pk_f32_fp4 v[56:57], v1, 1.0 op_sel:[1,1,0]
	v_pk_fma_f32 v[46:47], v[56:57], v[78:79], v[46:47]
	v_cvt_scalef32_pk_f32_fp4 v[56:57], v2, 1.0
	v_pk_fma_f32 v[46:47], v[56:57], v[80:81], v[46:47]
	v_cvt_scalef32_pk_f32_fp4 v[56:57], v2, 1.0 op_sel:[1,0,0]
	v_pk_fma_f32 v[46:47], v[56:57], v[82:83], v[46:47]
	v_cvt_scalef32_pk_f32_fp4 v[56:57], v2, 1.0 op_sel:[0,1,0]
	v_pk_fma_f32 v[46:47], v[56:57], v[84:85], v[46:47]
	v_cvt_scalef32_pk_f32_fp4 v[56:57], v2, 1.0 op_sel:[1,1,0]
	v_pk_fma_f32 v[46:47], v[56:57], v[86:87], v[46:47]
	v_cvt_scalef32_pk_f32_fp4 v[56:57], v3, 1.0
	v_pk_fma_f32 v[46:47], v[56:57], v[88:89], v[46:47]
	v_cvt_scalef32_pk_f32_fp4 v[56:57], v3, 1.0 op_sel:[1,0,0]
	v_pk_fma_f32 v[46:47], v[56:57], v[90:91], v[46:47]
	v_cvt_scalef32_pk_f32_fp4 v[56:57], v3, 1.0 op_sel:[0,1,0]
	v_pk_fma_f32 v[46:47], v[56:57], v[92:93], v[46:47]
	v_cvt_scalef32_pk_f32_fp4 v[56:57], v3, 1.0 op_sel:[1,1,0]
	v_pk_fma_f32 v[46:47], v[56:57], v[94:95], v[46:47]
	s_waitcnt vmcnt(12)
	v_cvt_scalef32_pk_f32_fp4 v[56:57], v4, 1.0 op_sel:[1,0,0]
	v_add_f32_e32 v58, v46, v47
	v_cvt_scalef32_pk_f32_fp4 v[46:47], v4, 1.0
	v_pk_fma_f32 v[46:47], v[46:47], v[64:65], 0 op_sel_hi:[1,1,0]
	s_waitcnt vmcnt(9)
	v_cvt_scalef32_pk_f32_fp4 v[114:115], v16, 1.0 op_sel:[1,0,0]
	v_pk_fma_f32 v[46:47], v[56:57], v[66:67], v[46:47]
	v_cvt_scalef32_pk_f32_fp4 v[56:57], v4, 1.0 op_sel:[0,1,0]
	v_pk_fma_f32 v[46:47], v[56:57], v[68:69], v[46:47]
	v_cvt_scalef32_pk_f32_fp4 v[56:57], v4, 1.0 op_sel:[1,1,0]
	v_pk_fma_f32 v[46:47], v[56:57], v[70:71], v[46:47]
	v_cvt_scalef32_pk_f32_fp4 v[56:57], v5, 1.0
	v_pk_fma_f32 v[46:47], v[56:57], v[72:73], v[46:47]
	v_cvt_scalef32_pk_f32_fp4 v[56:57], v5, 1.0 op_sel:[1,0,0]
	v_pk_fma_f32 v[46:47], v[56:57], v[74:75], v[46:47]
	v_cvt_scalef32_pk_f32_fp4 v[56:57], v5, 1.0 op_sel:[0,1,0]
	v_pk_fma_f32 v[46:47], v[56:57], v[76:77], v[46:47]
	v_cvt_scalef32_pk_f32_fp4 v[56:57], v5, 1.0 op_sel:[1,1,0]
	v_pk_fma_f32 v[46:47], v[56:57], v[78:79], v[46:47]
	v_cvt_scalef32_pk_f32_fp4 v[56:57], v6, 1.0
	v_pk_fma_f32 v[46:47], v[56:57], v[80:81], v[46:47]
	v_cvt_scalef32_pk_f32_fp4 v[56:57], v6, 1.0 op_sel:[1,0,0]
	v_pk_fma_f32 v[46:47], v[56:57], v[82:83], v[46:47]
	v_cvt_scalef32_pk_f32_fp4 v[56:57], v6, 1.0 op_sel:[0,1,0]
	v_pk_fma_f32 v[46:47], v[56:57], v[84:85], v[46:47]
	v_cvt_scalef32_pk_f32_fp4 v[56:57], v6, 1.0 op_sel:[1,1,0]
	v_pk_fma_f32 v[46:47], v[56:57], v[86:87], v[46:47]
	v_cvt_scalef32_pk_f32_fp4 v[56:57], v7, 1.0
	v_pk_fma_f32 v[46:47], v[56:57], v[88:89], v[46:47]
	v_cvt_scalef32_pk_f32_fp4 v[56:57], v7, 1.0 op_sel:[1,0,0]
	v_pk_fma_f32 v[46:47], v[56:57], v[90:91], v[46:47]
	v_cvt_scalef32_pk_f32_fp4 v[56:57], v7, 1.0 op_sel:[0,1,0]
	v_pk_fma_f32 v[46:47], v[56:57], v[92:93], v[46:47]
	v_cvt_scalef32_pk_f32_fp4 v[56:57], v7, 1.0 op_sel:[1,1,0]
	v_pk_fma_f32 v[46:47], v[56:57], v[94:95], v[46:47]
	v_cvt_scalef32_pk_f32_fp4 v[56:57], v8, 1.0 op_sel:[1,0,0]
	v_add_f32_e32 v59, v46, v47
	v_cvt_scalef32_pk_f32_fp4 v[46:47], v8, 1.0
	v_pk_fma_f32 v[46:47], v[46:47], v[64:65], 0 op_sel_hi:[1,1,0]
	s_add_i32 s4, s10, 14
	v_pk_fma_f32 v[46:47], v[56:57], v[66:67], v[46:47]
	v_cvt_scalef32_pk_f32_fp4 v[56:57], v8, 1.0 op_sel:[0,1,0]
	v_pk_fma_f32 v[46:47], v[56:57], v[68:69], v[46:47]
	v_cvt_scalef32_pk_f32_fp4 v[56:57], v8, 1.0 op_sel:[1,1,0]
	v_pk_fma_f32 v[46:47], v[56:57], v[70:71], v[46:47]
	v_cvt_scalef32_pk_f32_fp4 v[56:57], v9, 1.0
	v_pk_fma_f32 v[46:47], v[56:57], v[72:73], v[46:47]
	v_cvt_scalef32_pk_f32_fp4 v[56:57], v9, 1.0 op_sel:[1,0,0]
	v_pk_fma_f32 v[46:47], v[56:57], v[74:75], v[46:47]
	v_cvt_scalef32_pk_f32_fp4 v[56:57], v9, 1.0 op_sel:[0,1,0]
	v_pk_fma_f32 v[46:47], v[56:57], v[76:77], v[46:47]
	v_cvt_scalef32_pk_f32_fp4 v[56:57], v9, 1.0 op_sel:[1,1,0]
	v_pk_fma_f32 v[46:47], v[56:57], v[78:79], v[46:47]
	v_cvt_scalef32_pk_f32_fp4 v[56:57], v10, 1.0
	v_pk_fma_f32 v[46:47], v[56:57], v[80:81], v[46:47]
	v_cvt_scalef32_pk_f32_fp4 v[56:57], v10, 1.0 op_sel:[1,0,0]
	v_pk_fma_f32 v[46:47], v[56:57], v[82:83], v[46:47]
	v_cvt_scalef32_pk_f32_fp4 v[56:57], v10, 1.0 op_sel:[0,1,0]
	v_pk_fma_f32 v[46:47], v[56:57], v[84:85], v[46:47]
	v_cvt_scalef32_pk_f32_fp4 v[56:57], v10, 1.0 op_sel:[1,1,0]
	v_pk_fma_f32 v[46:47], v[56:57], v[86:87], v[46:47]
	v_cvt_scalef32_pk_f32_fp4 v[56:57], v11, 1.0
	v_pk_fma_f32 v[46:47], v[56:57], v[88:89], v[46:47]
	v_cvt_scalef32_pk_f32_fp4 v[56:57], v11, 1.0 op_sel:[1,0,0]
	v_pk_fma_f32 v[46:47], v[56:57], v[90:91], v[46:47]
	v_cvt_scalef32_pk_f32_fp4 v[56:57], v11, 1.0 op_sel:[0,1,0]
	v_pk_fma_f32 v[46:47], v[56:57], v[92:93], v[46:47]
	v_cvt_scalef32_pk_f32_fp4 v[56:57], v11, 1.0 op_sel:[1,1,0]
	v_pk_fma_f32 v[46:47], v[56:57], v[94:95], v[46:47]
	v_cvt_scalef32_pk_f32_fp4 v[56:57], v12, 1.0 op_sel:[1,0,0]
	v_add_f32_e32 v109, v46, v47
	v_cvt_scalef32_pk_f32_fp4 v[46:47], v12, 1.0
	v_pk_fma_f32 v[46:47], v[46:47], v[64:65], 0 op_sel_hi:[1,1,0]
	v_readlane_b32 s4, v108, s4
	v_pk_fma_f32 v[46:47], v[56:57], v[66:67], v[46:47]
	v_cvt_scalef32_pk_f32_fp4 v[56:57], v12, 1.0 op_sel:[0,1,0]
	v_pk_fma_f32 v[46:47], v[56:57], v[68:69], v[46:47]
	v_cvt_scalef32_pk_f32_fp4 v[56:57], v12, 1.0 op_sel:[1,1,0]
	v_pk_fma_f32 v[46:47], v[56:57], v[70:71], v[46:47]
	v_cvt_scalef32_pk_f32_fp4 v[56:57], v13, 1.0
	v_pk_fma_f32 v[46:47], v[56:57], v[72:73], v[46:47]
	v_cvt_scalef32_pk_f32_fp4 v[56:57], v13, 1.0 op_sel:[1,0,0]
	v_pk_fma_f32 v[46:47], v[56:57], v[74:75], v[46:47]
	v_cvt_scalef32_pk_f32_fp4 v[56:57], v13, 1.0 op_sel:[0,1,0]
	v_pk_fma_f32 v[46:47], v[56:57], v[76:77], v[46:47]
	v_cvt_scalef32_pk_f32_fp4 v[56:57], v13, 1.0 op_sel:[1,1,0]
	v_pk_fma_f32 v[46:47], v[56:57], v[78:79], v[46:47]
	v_cvt_scalef32_pk_f32_fp4 v[56:57], v14, 1.0
	v_pk_fma_f32 v[46:47], v[56:57], v[80:81], v[46:47]
	v_cvt_scalef32_pk_f32_fp4 v[56:57], v14, 1.0 op_sel:[1,0,0]
	v_pk_fma_f32 v[46:47], v[56:57], v[82:83], v[46:47]
	v_cvt_scalef32_pk_f32_fp4 v[56:57], v14, 1.0 op_sel:[0,1,0]
	v_pk_fma_f32 v[46:47], v[56:57], v[84:85], v[46:47]
	v_cvt_scalef32_pk_f32_fp4 v[56:57], v14, 1.0 op_sel:[1,1,0]
	v_pk_fma_f32 v[46:47], v[56:57], v[86:87], v[46:47]
	v_cvt_scalef32_pk_f32_fp4 v[56:57], v15, 1.0
	v_pk_fma_f32 v[46:47], v[56:57], v[88:89], v[46:47]
	v_cvt_scalef32_pk_f32_fp4 v[56:57], v15, 1.0 op_sel:[1,0,0]
	v_pk_fma_f32 v[46:47], v[56:57], v[90:91], v[46:47]
	v_cvt_scalef32_pk_f32_fp4 v[56:57], v15, 1.0 op_sel:[0,1,0]
	v_pk_fma_f32 v[46:47], v[56:57], v[92:93], v[46:47]
	v_cvt_scalef32_pk_f32_fp4 v[56:57], v15, 1.0 op_sel:[1,1,0]
	v_pk_fma_f32 v[46:47], v[56:57], v[94:95], v[46:47]
	v_cndmask_b32_e64 v57, v109, v58, s[0:1]
	v_add_f32_e32 v46, v46, v47
	v_cndmask_b32_e64 v47, v58, v109, s[0:1]
	v_cndmask_b32_e64 v56, v59, v46, s[0:1]
	ds_bpermute_b32 v47, v129, v47
	ds_bpermute_b32 v56, v129, v56
	v_cndmask_b32_e64 v46, v46, v59, s[0:1]
	s_ashr_i32 s5, s4, 31
	s_lshl_b64 s[4:5], s[4:5], 10
	s_waitcnt lgkmcnt(1)
	v_add_f32_e32 v109, v57, v47
	s_waitcnt lgkmcnt(0)
	v_add_f32_e32 v111, v46, v56
	v_cndmask_b32_e64 v46, v109, v111, s[2:3]
	ds_bpermute_b32 v112, v146, v46
	v_cndmask_b32_e64 v109, v111, v109, s[2:3]
	v_lshl_add_u64 v[44:45], v[98:99], 0, s[4:5]
	s_add_i32 s4, s10, 15
	v_readlane_b32 s4, v108, s4
	s_waitcnt lgkmcnt(0)
	v_add_f32_e32 v109, v109, v112
	v_cvt_scalef32_pk_f32_fp4 v[112:113], v16, 1.0
	v_pk_fma_f32 v[112:113], v[112:113], v[64:65], 0 op_sel_hi:[1,1,0]
	s_ashr_i32 s5, s4, 31
	v_pk_fma_f32 v[112:113], v[114:115], v[66:67], v[112:113]
	v_cvt_scalef32_pk_f32_fp4 v[114:115], v16, 1.0 op_sel:[0,1,0]
	v_pk_fma_f32 v[112:113], v[114:115], v[68:69], v[112:113]
	v_cvt_scalef32_pk_f32_fp4 v[114:115], v16, 1.0 op_sel:[1,1,0]
	v_pk_fma_f32 v[112:113], v[114:115], v[70:71], v[112:113]
	v_cvt_scalef32_pk_f32_fp4 v[114:115], v17, 1.0
	v_pk_fma_f32 v[112:113], v[114:115], v[72:73], v[112:113]
	v_cvt_scalef32_pk_f32_fp4 v[114:115], v17, 1.0 op_sel:[1,0,0]
	v_pk_fma_f32 v[112:113], v[114:115], v[74:75], v[112:113]
	v_cvt_scalef32_pk_f32_fp4 v[114:115], v17, 1.0 op_sel:[0,1,0]
	v_pk_fma_f32 v[112:113], v[114:115], v[76:77], v[112:113]
	v_cvt_scalef32_pk_f32_fp4 v[114:115], v17, 1.0 op_sel:[1,1,0]
	v_pk_fma_f32 v[112:113], v[114:115], v[78:79], v[112:113]
	v_cvt_scalef32_pk_f32_fp4 v[114:115], v18, 1.0
	v_pk_fma_f32 v[112:113], v[114:115], v[80:81], v[112:113]
	v_cvt_scalef32_pk_f32_fp4 v[114:115], v18, 1.0 op_sel:[1,0,0]
	s_lshl_b64 s[4:5], s[4:5], 10
	v_pk_fma_f32 v[112:113], v[114:115], v[82:83], v[112:113]
	v_cvt_scalef32_pk_f32_fp4 v[114:115], v18, 1.0 op_sel:[0,1,0]
	v_lshl_add_u64 v[46:47], v[98:99], 0, s[4:5]
	v_pk_fma_f32 v[112:113], v[114:115], v[84:85], v[112:113]
	v_cvt_scalef32_pk_f32_fp4 v[114:115], v18, 1.0 op_sel:[1,1,0]
	global_load_dwordx4 v[56:59], v[44:45], off
	s_nop 0
	global_load_dwordx4 v[44:47], v[46:47], off
	v_pk_fma_f32 v[112:113], v[114:115], v[86:87], v[112:113]
	v_cvt_scalef32_pk_f32_fp4 v[114:115], v19, 1.0
	v_pk_fma_f32 v[112:113], v[114:115], v[88:89], v[112:113]
	v_cvt_scalef32_pk_f32_fp4 v[114:115], v19, 1.0 op_sel:[1,0,0]
	v_pk_fma_f32 v[112:113], v[114:115], v[90:91], v[112:113]
	v_cvt_scalef32_pk_f32_fp4 v[114:115], v19, 1.0 op_sel:[0,1,0]
	v_pk_fma_f32 v[112:113], v[114:115], v[92:93], v[112:113]
	v_cvt_scalef32_pk_f32_fp4 v[114:115], v19, 1.0 op_sel:[1,1,0]
	v_pk_fma_f32 v[112:113], v[114:115], v[94:95], v[112:113]
	s_waitcnt vmcnt(10)
	v_cvt_scalef32_pk_f32_fp4 v[114:115], v20, 1.0 op_sel:[1,0,0]
	v_add_f32_e32 v111, v112, v113
	v_cvt_scalef32_pk_f32_fp4 v[112:113], v20, 1.0
	v_pk_fma_f32 v[112:113], v[112:113], v[64:65], 0 op_sel_hi:[1,1,0]
	v_add_f32_dpp v109, v109, v109 quad_perm:[1,0,3,2] row_mask:0xf bank_mask:0xf bound_ctrl:1
	v_pk_fma_f32 v[112:113], v[114:115], v[66:67], v[112:113]
	v_cvt_scalef32_pk_f32_fp4 v[114:115], v20, 1.0 op_sel:[0,1,0]
	v_pk_fma_f32 v[112:113], v[114:115], v[68:69], v[112:113]
	v_cvt_scalef32_pk_f32_fp4 v[114:115], v20, 1.0 op_sel:[1,1,0]
	v_pk_fma_f32 v[112:113], v[114:115], v[70:71], v[112:113]
	v_cvt_scalef32_pk_f32_fp4 v[114:115], v21, 1.0
	v_pk_fma_f32 v[112:113], v[114:115], v[72:73], v[112:113]
	v_cvt_scalef32_pk_f32_fp4 v[114:115], v21, 1.0 op_sel:[1,0,0]
	v_pk_fma_f32 v[112:113], v[114:115], v[74:75], v[112:113]
	v_cvt_scalef32_pk_f32_fp4 v[114:115], v21, 1.0 op_sel:[0,1,0]
	v_pk_fma_f32 v[112:113], v[114:115], v[76:77], v[112:113]
	v_cvt_scalef32_pk_f32_fp4 v[114:115], v21, 1.0 op_sel:[1,1,0]
	v_pk_fma_f32 v[112:113], v[114:115], v[78:79], v[112:113]
	v_cvt_scalef32_pk_f32_fp4 v[114:115], v22, 1.0
	v_pk_fma_f32 v[112:113], v[114:115], v[80:81], v[112:113]
	v_cvt_scalef32_pk_f32_fp4 v[114:115], v22, 1.0 op_sel:[1,0,0]
	v_pk_fma_f32 v[112:113], v[114:115], v[82:83], v[112:113]
	v_cvt_scalef32_pk_f32_fp4 v[114:115], v22, 1.0 op_sel:[0,1,0]
	v_pk_fma_f32 v[112:113], v[114:115], v[84:85], v[112:113]
	v_cvt_scalef32_pk_f32_fp4 v[114:115], v22, 1.0 op_sel:[1,1,0]
	v_pk_fma_f32 v[112:113], v[114:115], v[86:87], v[112:113]
	v_cvt_scalef32_pk_f32_fp4 v[114:115], v23, 1.0
	v_pk_fma_f32 v[112:113], v[114:115], v[88:89], v[112:113]
	v_cvt_scalef32_pk_f32_fp4 v[114:115], v23, 1.0 op_sel:[1,0,0]
	v_pk_fma_f32 v[112:113], v[114:115], v[90:91], v[112:113]
	v_cvt_scalef32_pk_f32_fp4 v[114:115], v23, 1.0 op_sel:[0,1,0]
	v_pk_fma_f32 v[112:113], v[114:115], v[92:93], v[112:113]
	v_cvt_scalef32_pk_f32_fp4 v[114:115], v23, 1.0 op_sel:[1,1,0]
	v_pk_fma_f32 v[112:113], v[114:115], v[94:95], v[112:113]
	s_waitcnt vmcnt(9)
	v_cvt_scalef32_pk_f32_fp4 v[114:115], v24, 1.0 op_sel:[1,0,0]
	v_add_f32_e32 v116, v112, v113
	v_cvt_scalef32_pk_f32_fp4 v[112:113], v24, 1.0
	v_pk_fma_f32 v[112:113], v[112:113], v[64:65], 0 op_sel_hi:[1,1,0]
	v_add_f32_dpp v109, v109, v109 quad_perm:[2,3,0,1] row_mask:0xf bank_mask:0xf bound_ctrl:1
	v_pk_fma_f32 v[112:113], v[114:115], v[66:67], v[112:113]
	v_cvt_scalef32_pk_f32_fp4 v[114:115], v24, 1.0 op_sel:[0,1,0]
	v_pk_fma_f32 v[112:113], v[114:115], v[68:69], v[112:113]
	v_cvt_scalef32_pk_f32_fp4 v[114:115], v24, 1.0 op_sel:[1,1,0]
	v_pk_fma_f32 v[112:113], v[114:115], v[70:71], v[112:113]
	v_cvt_scalef32_pk_f32_fp4 v[114:115], v25, 1.0
	v_pk_fma_f32 v[112:113], v[114:115], v[72:73], v[112:113]
	v_cvt_scalef32_pk_f32_fp4 v[114:115], v25, 1.0 op_sel:[1,0,0]
	v_pk_fma_f32 v[112:113], v[114:115], v[74:75], v[112:113]
	v_cvt_scalef32_pk_f32_fp4 v[114:115], v25, 1.0 op_sel:[0,1,0]
	v_pk_fma_f32 v[112:113], v[114:115], v[76:77], v[112:113]
	v_cvt_scalef32_pk_f32_fp4 v[114:115], v25, 1.0 op_sel:[1,1,0]
	v_pk_fma_f32 v[112:113], v[114:115], v[78:79], v[112:113]
	v_cvt_scalef32_pk_f32_fp4 v[114:115], v26, 1.0
	v_pk_fma_f32 v[112:113], v[114:115], v[80:81], v[112:113]
	v_cvt_scalef32_pk_f32_fp4 v[114:115], v26, 1.0 op_sel:[1,0,0]
	v_pk_fma_f32 v[112:113], v[114:115], v[82:83], v[112:113]
	v_cvt_scalef32_pk_f32_fp4 v[114:115], v26, 1.0 op_sel:[0,1,0]
	v_pk_fma_f32 v[112:113], v[114:115], v[84:85], v[112:113]
	v_cvt_scalef32_pk_f32_fp4 v[114:115], v26, 1.0 op_sel:[1,1,0]
	v_pk_fma_f32 v[112:113], v[114:115], v[86:87], v[112:113]
	v_cvt_scalef32_pk_f32_fp4 v[114:115], v27, 1.0
	v_pk_fma_f32 v[112:113], v[114:115], v[88:89], v[112:113]
	v_cvt_scalef32_pk_f32_fp4 v[114:115], v27, 1.0 op_sel:[1,0,0]
	v_pk_fma_f32 v[112:113], v[114:115], v[90:91], v[112:113]
	v_cvt_scalef32_pk_f32_fp4 v[114:115], v27, 1.0 op_sel:[0,1,0]
	v_pk_fma_f32 v[112:113], v[114:115], v[92:93], v[112:113]
	v_cvt_scalef32_pk_f32_fp4 v[114:115], v27, 1.0 op_sel:[1,1,0]
	v_pk_fma_f32 v[112:113], v[114:115], v[94:95], v[112:113]
	s_waitcnt vmcnt(8)
; #define PU_LOAD(BUF, EV, S0) do { _Pragma("unroll") for (int i = 0; i < 8; ++i) { const int row_ = __builtin_amdgcn_readlane(EV, (S0) + i); BUF[i & 3][i >> 2] = *(const u32x4*)(PU8 + (size_t)row_ * 1024 + lane * 16); } } while (0)
; __global__ void __launch_bounds__(NT, 2) mk_fwd(Args args) {
;     ...
;             float act0 = 0.f, act1 = 0.f;
;             u32x4 bA[4][2], bB[4][2];
; #pragma unroll
;             for (int hh = 0; hh < 2; ++hh) {
;                 const int ev = hh ? e1 : e0; const float gv = hh ? g1 : g0; float dv = 0.f;
;                 PU_LOAD(bA, ev, 0);
; #pragma unroll 1
;                 for (int s = 0; s < 64; s += 16) {
;                     PU_LOAD(bB, ev, s + 8);
;                     PU_DOT4(bA, 0, s); PU_DOT4(bA, 1, s + 4);
;                     if (s + 16 < 64) PU_LOAD(bA, ev, s + 16);
	v_cvt_scalef32_pk_f32_fp4 v[114:115], v28, 1.0 op_sel:[1,0,0]
	v_add_f32_e32 v117, v112, v113
	v_cvt_scalef32_pk_f32_fp4 v[112:113], v28, 1.0
	v_pk_fma_f32 v[112:113], v[112:113], v[64:65], 0 op_sel_hi:[1,1,0]
	v_add_f32_dpp v109, v109, v109 row_half_mirror row_mask:0xf bank_mask:0xf bound_ctrl:1
	v_pk_fma_f32 v[112:113], v[114:115], v[66:67], v[112:113]
	v_cvt_scalef32_pk_f32_fp4 v[114:115], v28, 1.0 op_sel:[0,1,0]
	v_pk_fma_f32 v[112:113], v[114:115], v[68:69], v[112:113]
	v_cvt_scalef32_pk_f32_fp4 v[114:115], v28, 1.0 op_sel:[1,1,0]
	v_pk_fma_f32 v[112:113], v[114:115], v[70:71], v[112:113]
	v_cvt_scalef32_pk_f32_fp4 v[114:115], v29, 1.0
	v_pk_fma_f32 v[112:113], v[114:115], v[72:73], v[112:113]
	v_cvt_scalef32_pk_f32_fp4 v[114:115], v29, 1.0 op_sel:[1,0,0]
	v_pk_fma_f32 v[112:113], v[114:115], v[74:75], v[112:113]
	v_cvt_scalef32_pk_f32_fp4 v[114:115], v29, 1.0 op_sel:[0,1,0]
	v_pk_fma_f32 v[112:113], v[114:115], v[76:77], v[112:113]
	v_cvt_scalef32_pk_f32_fp4 v[114:115], v29, 1.0 op_sel:[1,1,0]
	v_pk_fma_f32 v[112:113], v[114:115], v[78:79], v[112:113]
	v_cvt_scalef32_pk_f32_fp4 v[114:115], v30, 1.0
	v_pk_fma_f32 v[112:113], v[114:115], v[80:81], v[112:113]
	v_cvt_scalef32_pk_f32_fp4 v[114:115], v30, 1.0 op_sel:[1,0,0]
	v_pk_fma_f32 v[112:113], v[114:115], v[82:83], v[112:113]
	v_cvt_scalef32_pk_f32_fp4 v[114:115], v30, 1.0 op_sel:[0,1,0]
	v_pk_fma_f32 v[112:113], v[114:115], v[84:85], v[112:113]
	v_cvt_scalef32_pk_f32_fp4 v[114:115], v30, 1.0 op_sel:[1,1,0]
	v_pk_fma_f32 v[112:113], v[114:115], v[86:87], v[112:113]
	v_cvt_scalef32_pk_f32_fp4 v[114:115], v31, 1.0
	v_pk_fma_f32 v[112:113], v[114:115], v[88:89], v[112:113]
	v_cvt_scalef32_pk_f32_fp4 v[114:115], v31, 1.0 op_sel:[1,0,0]
	v_pk_fma_f32 v[112:113], v[114:115], v[90:91], v[112:113]
	v_cvt_scalef32_pk_f32_fp4 v[114:115], v31, 1.0 op_sel:[0,1,0]
	v_pk_fma_f32 v[112:113], v[114:115], v[92:93], v[112:113]
	v_cvt_scalef32_pk_f32_fp4 v[114:115], v31, 1.0 op_sel:[1,1,0]
	v_pk_fma_f32 v[112:113], v[114:115], v[94:95], v[112:113]
	v_add_f32_dpp v109, v109, v109 row_mirror row_mask:0xf bank_mask:0xf bound_ctrl:1
	v_add_f32_e32 v112, v112, v113
	v_cndmask_b32_e64 v113, v111, v117, s[0:1]
	v_cndmask_b32_e64 v114, v116, v112, s[0:1]
	ds_bpermute_b32 v113, v129, v113
	ds_bpermute_b32 v114, v129, v114
	v_cndmask_b32_e64 v111, v117, v111, s[0:1]
	v_cndmask_b32_e64 v112, v112, v116, s[0:1]
	s_add_i32 s12, s10, 16
	s_waitcnt lgkmcnt(1)
	v_add_f32_e32 v113, v111, v113
	s_waitcnt lgkmcnt(0)
	v_add_f32_e32 v112, v112, v114
	v_cndmask_b32_e64 v111, v113, v112, s[2:3]
	ds_bpermute_b32 v114, v146, v111
	ds_bpermute_b32 v111, v147, v109
	v_cndmask_b32_e64 v109, v112, v113, s[2:3]
	s_cmp_gt_u32 s10, 47
	s_cselect_b64 s[4:5], -1, 0
	s_waitcnt lgkmcnt(1)
	v_add_f32_e32 v109, v109, v114
	s_cmp_lt_u32 s10, 48
	s_nop 0
	v_add_f32_dpp v109, v109, v109 quad_perm:[1,0,3,2] row_mask:0xf bank_mask:0xf bound_ctrl:1
	s_nop 1
	v_add_f32_dpp v109, v109, v109 quad_perm:[2,3,0,1] row_mask:0xf bank_mask:0xf bound_ctrl:1
	s_nop 1
	v_add_f32_dpp v109, v109, v109 row_half_mirror row_mask:0xf bank_mask:0xf bound_ctrl:1
	s_nop 1
	v_add_f32_dpp v109, v109, v109 row_mirror row_mask:0xf bank_mask:0xf bound_ctrl:1
	ds_bpermute_b32 v109, v147, v109
	s_cbranch_scc0 .Lp10_dmy_889
	v_readlane_b32 s30, v108, s12
	s_ashr_i32 s31, s30, 31
	s_lshl_b64 s[30:31], s[30:31], 10
	s_add_i32 s14, s10, 17
	v_lshl_add_u64 v[8:9], v[98:99], 0, s[30:31]
	v_readlane_b32 s30, v108, s14
	s_ashr_i32 s31, s30, 31
	s_lshl_b64 s[30:31], s[30:31], 10
	s_add_i32 s14, s10, 18
	v_lshl_add_u64 v[10:11], v[98:99], 0, s[30:31]
	v_readlane_b32 s30, v108, s14
	s_ashr_i32 s31, s30, 31
	s_lshl_b64 s[30:31], s[30:31], 10
	s_add_i32 s14, s10, 19
	v_lshl_add_u64 v[16:17], v[98:99], 0, s[30:31]
	v_readlane_b32 s30, v108, s14
	s_ashr_i32 s31, s30, 31
	s_lshl_b64 s[30:31], s[30:31], 10
	s_add_i32 s14, s10, 20
	v_lshl_add_u64 v[18:19], v[98:99], 0, s[30:31]
	v_readlane_b32 s30, v108, s14
	s_ashr_i32 s31, s30, 31
	s_lshl_b64 s[30:31], s[30:31], 10
	s_add_i32 s14, s10, 21
	v_lshl_add_u64 v[24:25], v[98:99], 0, s[30:31]
	v_readlane_b32 s30, v108, s14
	s_ashr_i32 s31, s30, 31
	s_lshl_b64 s[30:31], s[30:31], 10
	s_add_i32 s14, s10, 22
	v_lshl_add_u64 v[26:27], v[98:99], 0, s[30:31]
	v_readlane_b32 s30, v108, s14
	s_ashr_i32 s31, s30, 31
	s_lshl_b64 s[30:31], s[30:31], 10
	s_add_i32 s14, s10, 23
	global_load_dwordx4 v[0:3], v[8:9], off
	global_load_dwordx4 v[4:7], v[10:11], off
	s_nop 0
	global_load_dwordx4 v[8:11], v[16:17], off
	global_load_dwordx4 v[12:15], v[18:19], off
	s_nop 0
	global_load_dwordx4 v[16:19], v[24:25], off
	global_load_dwordx4 v[20:23], v[26:27], off
	v_lshl_add_u64 v[24:25], v[98:99], 0, s[30:31]
	v_readlane_b32 s30, v108, s14
	s_ashr_i32 s31, s30, 31
	s_lshl_b64 s[30:31], s[30:31], 10
	v_lshl_add_u64 v[28:29], v[98:99], 0, s[30:31]
	global_load_dwordx4 v[24:27], v[24:25], off
	s_nop 0
	global_load_dwordx4 v[28:31], v[28:29], off
	s_branch .LBB0_889
